# row-scale table build restricted to the 256 rows this workgroup's epilogues use (1 loop pass instead of 4, 1/8 of the partial-sum loads), on top of k-snake + scalar-base DMA addressing
# speedup vs baseline: 1.0135x; 1.0121x over previous
.LBB0_157:
	v_mov_b32_e32 v0, v156
	s_movk_i32 s0, 0x800
	s_nop 0
	v_cmp_gt_i32_e32 vcc, s0, v0
	s_and_saveexec_b64 s[0:1], vcc
	s_cbranch_execz .LBB0_160
	s_lshl_b32 s26, s2, 8
	s_and_b32 s28, s26, 0xfffff800
	v_readlane_b32 s26, v241, 6
	v_readlane_b32 s27, v241, 7
	s_and_b64 s[26:27], s[26:27], exec
	s_cselect_b32 s26, s28, 0
	v_add_u32_e32 v3, 0xfffffe00, v0
	v_lshl_add_u32 v4, v0, 2, s92
	v_add_u32_e32 v0, s26, v0
	v_ashrrev_i32_e32 v1, 31, v0
	s_add_u32 s26, s24, s12
	v_lshlrev_b64 v[0:1], 7, v[0:1]
	s_addc_u32 s27, s25, s13
	s_and_b32 s28, s2, 7
	s_lshr_b32 s29, s28, 1
	s_and_b32 s28, s28, 1
	v_lshrrev_b32_e32 v5, 8, v156
	v_cmp_eq_u32_e32 vcc, s28, v5
	s_and_b64 exec, exec, vcc
	s_lshl_b32 s29, s29, 9
	v_lshl_add_u32 v4, s29, 2, v4
	s_lshl_b32 s28, s29, 7
	s_mov_b32 s29, 0
	v_lshl_add_u64 v[0:1], v[0:1], 0, s[28:29]
	s_mov_b64 s[28:29], -1

.LBB0_230:
	s_and_b64 vcc, exec, s[0:1]
	s_cbranch_vccz .LBB0_345
	v_readlane_b32 s0, v241, 44
	v_readlane_b32 s1, v241, 45
	s_andn2_b64 vcc, exec, s[0:1]
	s_nop 0
	v_cndmask_b32_e64 v0, 0, 1, s[0:1]
	v_cmp_ne_u32_e64 s[38:39], 1, v0
	v_mov_b32_e32 v0, v156
	s_movk_i32 s0, 0x800
	s_nop 0
	v_cmp_gt_i32_e32 vcc, s0, v0
	s_and_saveexec_b64 s[0:1], vcc
	s_cbranch_execz .LBB0_234
	v_readlane_b32 s2, v240, 5
	s_lshl_b32 s2, s2, 8
	v_readlane_b32 s26, v241, 44
	s_and_b32 s2, s2, 0xfffff800
	v_readlane_b32 s27, v241, 45
	s_and_b64 s[26:27], s[26:27], exec
	s_cselect_b32 s2, s2, 0
	v_add_u32_e32 v3, 0xfffffe00, v0
	v_lshl_add_u32 v4, v0, 2, s92
	v_add_u32_e32 v0, s2, v0
	v_ashrrev_i32_e32 v1, 31, v0
	s_add_u32 s26, s24, s12
	v_lshlrev_b64 v[0:1], 7, v[0:1]
	s_addc_u32 s27, s25, s13
	v_readlane_b32 s28, v240, 5
	s_nop 0
	s_and_b32 s28, s28, 7
	s_lshr_b32 s29, s28, 1
	s_and_b32 s28, s28, 1
	v_lshrrev_b32_e32 v5, 8, v156
	v_cmp_eq_u32_e32 vcc, s28, v5
	s_and_b64 exec, exec, vcc
	s_lshl_b32 s29, s29, 9
	v_lshl_add_u32 v4, s29, 2, v4
	s_lshl_b32 s28, s29, 7
	s_mov_b32 s29, 0
	v_lshl_add_u64 v[0:1], v[0:1], 0, s[28:29]
	s_mov_b64 s[28:29], -1
